# priority for the other wave half (slot != 0) during the mixers-phase-A compute items, slot-0 raise kept in attention/queue and LayerNorm phases
# speedup vs baseline: 1.0132x; 1.0132x over previous
.LBB0_332:
	s_cmp_eq_u32 s101, 3
	s_cbranch_scc1 .Lma_fin
	s_getreg_b32 s100, hwreg(HW_REG_HW_ID, 0, 4)
	s_cmp_lg_u32 s100, 0
	s_cbranch_scc0 .Lprio_done_s3
	s_setprio 1

.LBB0_542:
	s_or_b64 exec, exec, s[2:3]
	s_waitcnt lgkmcnt(0)
	s_barrier
	s_setprio 0
.LBB0_543:
	v_readlane_b32 s0, v255, 26
	s_or_b32 s2, s0, 3
	v_readlane_b32 s4, v254, 3
	v_readlane_b32 s5, v254, 4
	s_cmp_le_i32 s4, s2
	s_cselect_b64 s[0:1], -1, 0
	s_cmp_lt_i32 s2, s5
	s_cselect_b64 s[2:3], -1, 0
	s_and_b64 s[0:1], s[0:1], s[2:3]
	s_andn2_b64 vcc, exec, s[0:1]
	s_cbranch_vccnz .LBB0_840
	s_mov_b32 s2, s23
	s_getreg_b32 s0, hwreg(HW_REG_HW_ID, 0, 6)
	v_readlane_b32 s15, v254, 2
	v_mbcnt_lo_u32_b32 v0, -1, 0
	v_mbcnt_hi_u32_b32 v0, -1, v0
	s_and_b32 s0, s15, 7
	s_mov_b32 s19, s92
	s_cmp_lg_u32 s0, 0
	s_cbranch_scc0 .LBB0_546
	s_cmpk_gt_i32 s19, 0xff
	s_cbranch_scc0 .LBB0_547
	s_branch .LBB0_629
